# v032 stack + diagonal causal-mask compare/select regrouped over three mask registers (no per-element s_nop)
# baseline (speedup 1.0000x reference)
; #define LAS __attribute__((address_space(3)))
; __device__ __forceinline__ int crow(int r, int hi) { return (r & 3) + 8 * (r >> 2) + 4 * hi; }
; #define MFMA32(a, b, c) __builtin_amdgcn_mfma_f32_32x32x16_bf16((a), (b), (c), 0, 0, 0)
; template <bool QLDS> __device__ __forceinline__ void attn_tile(const LAS unsigned char* buf, const bf16x8 (&qf)[4], const LAS bf16x8* qlds, float cq2, int qpos, int kv0, bool diag, float& mrun, float& lrun, f32x16 (&ot)[2], int l31, int hi) {
;     ...
;     f32x16 p0, p1;
; #pragma unroll
;     for (int r = 0; r < 16; ++r) { p0[r] = cq2; p1[r] = cq2; }
;     {
;         const u32x2 b0 = CKs[l31], b1 = CKs[32 + l31];
;         const unsigned msk = hi ? 0u : 0xffffffffu;
;         u32x4 x0; x0.x = b0.x & msk; x0.y = b0.y & msk; x0.z = 0u; x0.w = 0u;
;         u32x4 x1; x1.x = b1.x & msk; x1.y = b1.y & msk; x1.z = 0u; x1.w = 0u;
;         u32x4 qx; qx.x = 0x3F803F80u & msk; qx.y = 0x00003F80u & msk; qx.z = 0u; qx.w = 0u;
;         p0 = MFMA32(__builtin_bit_cast(bf16x8, x0), __builtin_bit_cast(bf16x8, qx), p0); p1 = MFMA32(__builtin_bit_cast(bf16x8, x1), __builtin_bit_cast(bf16x8, qx), p1);
;     }
; #pragma unroll
;     for (int ks = 0; ks < 4; ++ks) { const bf16x8 k0 = *(const LAS bf16x8*)(Ks + l31 * AT_KS + 16 * ks + 8 * hi), k1 = *(const LAS bf16x8*)(Ks + (32 + l31) * AT_KS + 16 * ks + 8 * hi);
;         const bf16x8 qq = QLDS ? qlds[ks * 64] : qf[ks];
;         p0 = MFMA32(k0, qq, p0); p1 = MFMA32(k1, qq, p1); }
;     __builtin_amdgcn_sched_barrier(0);
;     if (diag) {
;         int qp = qpos - kv0; asm volatile("" : "+v"(qp));
; #pragma unroll
;         for (int r = 0; r < 16; ++r) { const int kv = crow(r, hi); if (kv > qp) p0[r] = -INFINITY; if (kv + 32 > qp) p1[r] = -INFINITY; }
;     }
.LBB0_1651:
	s_andn2_b64 vcc, exec, s[72:73]
	s_cbranch_vccnz .LBB0_1650
	s_bitcmp1_b32 s14, 0
	s_cselect_b32 s58, 0x4800, 0
	s_add_i32 s58, s58, 0
	v_lshl_add_u32 v50, v107, 3, s58
	v_add_u32_e32 v50, 0x4000, v50
	ds_read2_b64 v[50:53], v50 offset0:192 offset1:224
	v_mov_b32_e32 v66, v67
	v_mov_b32_e32 v154, v67
	v_mov_b32_e32 v155, v67
	s_cmp_lg_u32 s14, 0
	s_waitcnt lgkmcnt(0)
	v_and_b32_e32 v64, v50, v111
	v_and_b32_e32 v65, v51, v111
	v_and_b32_e32 v152, v52, v111
	v_and_b32_e32 v153, v53, v111
	v_mfma_f32_32x32x16_bf16 v[68:83], v[64:67], v[84:87], v[34:49]
	v_lshlrev_b32_e32 v66, 1, v110
	v_add3_u32 v147, s58, v112, v66
	v_add3_u32 v66, s58, v113, v66
	ds_read_b128 v[156:159], v147 offset:32
	v_mfma_f32_32x32x16_bf16 v[50:65], v[152:155], v[84:87], v[34:49]
	ds_read_b128 v[152:155], v147
	s_waitcnt vmcnt(3) lgkmcnt(0)
	v_mfma_f32_32x32x16_bf16 v[68:83], v[152:155], v[88:91], v[68:83]
	ds_read_b128 v[152:155], v66
	ds_read_b128 v[160:163], v66 offset:32
	s_waitcnt lgkmcnt(1)
	v_mfma_f32_32x32x16_bf16 v[50:65], v[152:155], v[88:91], v[50:65]
	s_waitcnt vmcnt(2)
	v_mfma_f32_32x32x16_bf16 v[68:83], v[156:159], v[92:95], v[68:83]
	ds_read_b128 v[152:155], v147 offset:64
	ds_read_b128 v[156:159], v147 offset:96
	s_waitcnt lgkmcnt(2)
	v_mfma_f32_32x32x16_bf16 v[50:65], v[160:163], v[92:95], v[50:65]
	s_waitcnt vmcnt(1) lgkmcnt(1)
	v_mfma_f32_32x32x16_bf16 v[68:83], v[152:155], v[96:99], v[68:83]
	ds_read_b128 v[152:155], v66 offset:64
	ds_read_b128 v[160:163], v66 offset:96
	s_waitcnt lgkmcnt(1)
	v_mfma_f32_32x32x16_bf16 v[50:65], v[152:155], v[96:99], v[50:65]
	s_waitcnt vmcnt(0)
	v_mfma_f32_32x32x16_bf16 v[68:83], v[156:159], v[100:103], v[68:83]
	s_waitcnt lgkmcnt(0)
	v_mfma_f32_32x32x16_bf16 v[50:65], v[160:163], v[100:103], v[50:65]
	s_cbranch_scc1 .LBB0_1654
	v_mov_b32_e32 v66, v108
	s_nop 0
	v_cmp_le_i32_e64 s[98:99], v115, v66
	v_cmp_lt_i32_e64 s[100:101], v109, v66
	v_cmp_le_i32_e32 vcc, v109, v66
	s_nop 7
	v_cndmask_b32_e64 v50, v149, v50, s[98:99]
	v_cndmask_b32_e64 v69, v149, v69, s[100:101]
	v_cndmask_b32_e32 v68, v149, v68, vcc
	v_cmp_le_i32_e64 s[98:99], v116, v66
	v_cmp_le_i32_e64 s[100:101], v117, v66
	v_cmp_le_i32_e32 vcc, v118, v66
	v_cndmask_b32_e64 v51, v149, v51, s[98:99]
	v_cndmask_b32_e64 v70, v149, v70, s[100:101]
	v_cndmask_b32_e32 v52, v149, v52, vcc
	v_cmp_le_i32_e64 s[98:99], v119, v66
	v_cmp_le_i32_e64 s[100:101], v120, v66
	v_cmp_le_i32_e32 vcc, v121, v66
	v_cndmask_b32_e64 v71, v149, v71, s[98:99]
	v_cndmask_b32_e64 v53, v149, v53, s[100:101]
	v_cndmask_b32_e32 v72, v149, v72, vcc
	v_cmp_le_i32_e64 s[98:99], v122, v66
	v_cmp_le_i32_e64 s[100:101], v123, v66
	v_cmp_le_i32_e32 vcc, v124, v66
	v_cndmask_b32_e64 v54, v149, v54, s[98:99]
	v_cndmask_b32_e64 v73, v149, v73, s[100:101]
	v_cndmask_b32_e32 v55, v149, v55, vcc
	v_cmp_le_i32_e64 s[98:99], v125, v66
	v_cmp_le_i32_e64 s[100:101], v126, v66
	v_cmp_le_i32_e32 vcc, v127, v66
	v_cndmask_b32_e64 v74, v149, v74, s[98:99]
	v_cndmask_b32_e64 v56, v149, v56, s[100:101]
	v_cndmask_b32_e32 v75, v149, v75, vcc
	v_cmp_le_i32_e64 s[98:99], v128, v66
	v_cmp_le_i32_e64 s[100:101], v129, v66
	v_cmp_le_i32_e32 vcc, v130, v66
	v_cndmask_b32_e64 v57, v149, v57, s[98:99]
	v_cndmask_b32_e64 v76, v149, v76, s[100:101]
	v_cndmask_b32_e32 v58, v149, v58, vcc
	v_cmp_le_i32_e64 s[98:99], v131, v66
	v_cmp_le_i32_e64 s[100:101], v132, v66
	v_cmp_le_i32_e32 vcc, v133, v66
	v_cndmask_b32_e64 v77, v149, v77, s[98:99]
	v_cndmask_b32_e64 v59, v149, v59, s[100:101]
	v_cndmask_b32_e32 v78, v149, v78, vcc
	v_cmp_le_i32_e64 s[98:99], v134, v66
	v_cmp_le_i32_e64 s[100:101], v135, v66
	v_cmp_le_i32_e32 vcc, v136, v66
	v_cndmask_b32_e64 v60, v149, v60, s[98:99]
	v_cndmask_b32_e64 v79, v149, v79, s[100:101]
	v_cndmask_b32_e32 v61, v149, v61, vcc
	v_cmp_le_i32_e64 s[98:99], v137, v66
	v_cmp_le_i32_e64 s[100:101], v138, v66
	v_cmp_le_i32_e32 vcc, v139, v66
	v_cndmask_b32_e64 v80, v149, v80, s[98:99]
	v_cndmask_b32_e64 v62, v149, v62, s[100:101]
	v_cndmask_b32_e32 v81, v149, v81, vcc
	v_cmp_le_i32_e64 s[98:99], v140, v66
	v_cmp_le_i32_e64 s[100:101], v141, v66
	v_cmp_le_i32_e32 vcc, v142, v66
	v_cndmask_b32_e64 v63, v149, v63, s[98:99]
	v_cndmask_b32_e64 v82, v149, v82, s[100:101]
	v_cndmask_b32_e32 v64, v149, v64, vcc
	v_cmp_le_i32_e64 s[98:99], v143, v66
	v_cmp_le_i32_e32 vcc, v144, v66
	s_nop 0
	v_cndmask_b32_e64 v83, v149, v83, s[98:99]
	v_cndmask_b32_e32 v65, v149, v65, vcc

; #define LAS __attribute__((address_space(3)))
; __device__ __forceinline__ int crow(int r, int hi) { return (r & 3) + 8 * (r >> 2) + 4 * hi; }
; #define MFMA32(a, b, c) __builtin_amdgcn_mfma_f32_32x32x16_bf16((a), (b), (c), 0, 0, 0)
; template <bool QLDS> __device__ __forceinline__ void attn_tile(const LAS unsigned char* buf, const bf16x8 (&qf)[4], const LAS bf16x8* qlds, float cq2, int qpos, int kv0, bool diag, float& mrun, float& lrun, f32x16 (&ot)[2], int l31, int hi) {
;     ...
;     f32x16 p0, p1;
; #pragma unroll
;     for (int r = 0; r < 16; ++r) { p0[r] = cq2; p1[r] = cq2; }
;     {
;         const u32x2 b0 = CKs[l31], b1 = CKs[32 + l31];
;         const unsigned msk = hi ? 0u : 0xffffffffu;
;         u32x4 x0; x0.x = b0.x & msk; x0.y = b0.y & msk; x0.z = 0u; x0.w = 0u;
;         u32x4 x1; x1.x = b1.x & msk; x1.y = b1.y & msk; x1.z = 0u; x1.w = 0u;
;         u32x4 qx; qx.x = 0x3F803F80u & msk; qx.y = 0x00003F80u & msk; qx.z = 0u; qx.w = 0u;
;         p0 = MFMA32(__builtin_bit_cast(bf16x8, x0), __builtin_bit_cast(bf16x8, qx), p0); p1 = MFMA32(__builtin_bit_cast(bf16x8, x1), __builtin_bit_cast(bf16x8, qx), p1);
;     }
; #pragma unroll
;     for (int ks = 0; ks < 4; ++ks) { const bf16x8 k0 = *(const LAS bf16x8*)(Ks + l31 * AT_KS + 16 * ks + 8 * hi), k1 = *(const LAS bf16x8*)(Ks + (32 + l31) * AT_KS + 16 * ks + 8 * hi);
;         const bf16x8 qq = QLDS ? qlds[ks * 64] : qf[ks];
;         p0 = MFMA32(k0, qq, p0); p1 = MFMA32(k1, qq, p1); }
;     __builtin_amdgcn_sched_barrier(0);
;     if (diag) {
;         int qp = qpos - kv0; asm volatile("" : "+v"(qp));
; #pragma unroll
;         for (int r = 0; r < 16; ++r) { const int kv = crow(r, hi); if (kv > qp) p0[r] = -INFINITY; if (kv + 32 > qp) p1[r] = -INFINITY; }
;     }
.LBB0_1681:
	s_add_i32 s14, s92, 0x80
	s_cmp_gt_i32 s14, s76
	s_cbranch_scc1 .LBB0_1689
	s_add_i32 s71, s91, 6
	s_bitcmp1_b32 s77, 0
	s_cselect_b32 s14, 0x4800, 0
	s_add_i32 s14, s14, 0
	v_lshl_add_u32 v50, v139, 3, s14
	v_add_u32_e32 v50, 0x4000, v50
	ds_read2_b64 v[68:71], v50 offset0:192 offset1:224
	v_mov_b32_e32 v74, v67
	v_mov_b32_e32 v75, v67
	v_mov_b32_e32 v206, v67
	v_mov_b32_e32 v207, v67
	s_waitcnt lgkmcnt(0)
	v_and_b32_e32 v72, v68, v147
	v_and_b32_e32 v73, v69, v147
	v_and_b32_e32 v204, v70, v147
	v_and_b32_e32 v205, v71, v147
	v_lshlrev_b32_e32 v123, 1, v145
	v_add3_u32 v203, s14, v152, v123
	v_mfma_f32_32x32x16_bf16 v[50:65], v[72:75], v[112:115], v[18:33]
	v_add3_u32 v123, s14, v153, v123
	ds_read_b128 v[208:211], v203 offset:32
	s_cmp_lt_i32 s71, s57
	v_mfma_f32_32x32x16_bf16 v[68:83], v[204:207], v[112:115], v[18:33]
	ds_read_b128 v[204:207], v203
	s_waitcnt lgkmcnt(0)
	v_mfma_f32_32x32x16_bf16 v[50:65], v[204:207], v[84:87], v[50:65]
	ds_read_b128 v[204:207], v123
	ds_read_b128 v[212:215], v123 offset:32
	s_waitcnt lgkmcnt(1)
	v_mfma_f32_32x32x16_bf16 v[68:83], v[204:207], v[84:87], v[68:83]
	v_mfma_f32_32x32x16_bf16 v[50:65], v[208:211], v[88:91], v[50:65]
	ds_read_b128 v[204:207], v203 offset:64
	ds_read_b128 v[208:211], v203 offset:96
	s_waitcnt lgkmcnt(2)
	v_mfma_f32_32x32x16_bf16 v[68:83], v[212:215], v[88:91], v[68:83]
	s_waitcnt lgkmcnt(1)
	v_mfma_f32_32x32x16_bf16 v[50:65], v[204:207], v[92:95], v[50:65]
	ds_read_b128 v[204:207], v123 offset:64
	ds_read_b128 v[212:215], v123 offset:96
	s_waitcnt lgkmcnt(1)
	v_mfma_f32_32x32x16_bf16 v[68:83], v[204:207], v[92:95], v[68:83]
	v_mfma_f32_32x32x16_bf16 v[50:65], v[208:211], v[96:99], v[50:65]
	s_waitcnt lgkmcnt(0)
	v_mfma_f32_32x32x16_bf16 v[68:83], v[212:215], v[96:99], v[68:83]
	s_cbranch_scc1 .LBB0_1684
	v_add_u32_e32 v123, 0xffffff80, v200
	s_nop 0
	v_cmp_le_i32_e64 s[98:99], v154, v123
	v_cmp_lt_i32_e64 s[100:101], v146, v123
	v_cmp_le_i32_e32 vcc, v146, v123
	s_nop 7
	v_cndmask_b32_e64 v68, v149, v68, s[98:99]
	v_cndmask_b32_e64 v51, v149, v51, s[100:101]
	v_cndmask_b32_e32 v50, v149, v50, vcc
	v_cmp_le_i32_e64 s[98:99], v155, v123
	v_cmp_le_i32_e64 s[100:101], v156, v123
	v_cmp_le_i32_e32 vcc, v157, v123
	v_cndmask_b32_e64 v69, v149, v69, s[98:99]
	v_cndmask_b32_e64 v52, v149, v52, s[100:101]
	v_cndmask_b32_e32 v70, v149, v70, vcc
	v_cmp_le_i32_e64 s[98:99], v158, v123
	v_cmp_le_i32_e64 s[100:101], v159, v123
	v_cmp_le_i32_e32 vcc, v160, v123
	v_cndmask_b32_e64 v53, v149, v53, s[98:99]
	v_cndmask_b32_e64 v71, v149, v71, s[100:101]
	v_cndmask_b32_e32 v54, v149, v54, vcc
	v_cmp_le_i32_e64 s[98:99], v161, v123
	v_cmp_le_i32_e64 s[100:101], v162, v123
	v_cmp_le_i32_e32 vcc, v163, v123
	v_cndmask_b32_e64 v72, v149, v72, s[98:99]
	v_cndmask_b32_e64 v55, v149, v55, s[100:101]
	v_cndmask_b32_e32 v73, v149, v73, vcc
	v_cmp_le_i32_e64 s[98:99], v164, v123
	v_cmp_le_i32_e64 s[100:101], v165, v123
	v_cmp_le_i32_e32 vcc, v166, v123
	v_cndmask_b32_e64 v56, v149, v56, s[98:99]
	v_cndmask_b32_e64 v74, v149, v74, s[100:101]
	v_cndmask_b32_e32 v57, v149, v57, vcc
	v_cmp_le_i32_e64 s[98:99], v167, v123
	v_cmp_le_i32_e64 s[100:101], v183, v123
	v_cmp_le_i32_e32 vcc, v184, v123
	v_cndmask_b32_e64 v75, v149, v75, s[98:99]
	v_cndmask_b32_e64 v58, v149, v58, s[100:101]
	v_cndmask_b32_e32 v76, v149, v76, vcc
	v_cmp_le_i32_e64 s[98:99], v185, v123
	v_cmp_le_i32_e64 s[100:101], v186, v123
	v_cmp_le_i32_e32 vcc, v187, v123
	v_cndmask_b32_e64 v59, v149, v59, s[98:99]
	v_cndmask_b32_e64 v77, v149, v77, s[100:101]
	v_cndmask_b32_e32 v60, v149, v60, vcc
	v_cmp_le_i32_e64 s[98:99], v188, v123
	v_cmp_le_i32_e64 s[100:101], v189, v123
	v_cmp_le_i32_e32 vcc, v190, v123
	v_cndmask_b32_e64 v78, v149, v78, s[98:99]
	v_cndmask_b32_e64 v61, v149, v61, s[100:101]
	v_cndmask_b32_e32 v79, v149, v79, vcc
	v_cmp_le_i32_e64 s[98:99], v191, v123
	v_cmp_le_i32_e64 s[100:101], v192, v123
	v_cmp_le_i32_e32 vcc, v193, v123
	v_cndmask_b32_e64 v62, v149, v62, s[98:99]
	v_cndmask_b32_e64 v80, v149, v80, s[100:101]
	v_cndmask_b32_e32 v63, v149, v63, vcc
	v_cmp_le_i32_e64 s[98:99], v194, v123
	v_cmp_le_i32_e64 s[100:101], v195, v123
	v_cmp_le_i32_e32 vcc, v196, v123
	v_cndmask_b32_e64 v81, v149, v81, s[98:99]
	v_cndmask_b32_e64 v64, v149, v64, s[100:101]
	v_cndmask_b32_e32 v82, v149, v82, vcc
	v_cmp_le_i32_e64 s[98:99], v197, v123
	v_cmp_le_i32_e32 vcc, v198, v123
	s_nop 0
	v_cndmask_b32_e64 v65, v149, v65, s[98:99]
	v_cndmask_b32_e32 v83, v149, v83, vcc

; #define LAS __attribute__((address_space(3)))
; __device__ __forceinline__ int crow(int r, int hi) { return (r & 3) + 8 * (r >> 2) + 4 * hi; }
; #define MFMA32(a, b, c) __builtin_amdgcn_mfma_f32_32x32x16_bf16((a), (b), (c), 0, 0, 0)
; template <bool QLDS> __device__ __forceinline__ void attn_tile(const LAS unsigned char* buf, const bf16x8 (&qf)[4], const LAS bf16x8* qlds, float cq2, int qpos, int kv0, bool diag, float& mrun, float& lrun, f32x16 (&ot)[2], int l31, int hi) {
;     ...
;     f32x16 p0, p1;
; #pragma unroll
;     for (int r = 0; r < 16; ++r) { p0[r] = cq2; p1[r] = cq2; }
;     {
;         const u32x2 b0 = CKs[l31], b1 = CKs[32 + l31];
;         const unsigned msk = hi ? 0u : 0xffffffffu;
;         u32x4 x0; x0.x = b0.x & msk; x0.y = b0.y & msk; x0.z = 0u; x0.w = 0u;
;         u32x4 x1; x1.x = b1.x & msk; x1.y = b1.y & msk; x1.z = 0u; x1.w = 0u;
;         u32x4 qx; qx.x = 0x3F803F80u & msk; qx.y = 0x00003F80u & msk; qx.z = 0u; qx.w = 0u;
;         p0 = MFMA32(__builtin_bit_cast(bf16x8, x0), __builtin_bit_cast(bf16x8, qx), p0); p1 = MFMA32(__builtin_bit_cast(bf16x8, x1), __builtin_bit_cast(bf16x8, qx), p1);
;     }
; #pragma unroll
;     for (int ks = 0; ks < 4; ++ks) { const bf16x8 k0 = *(const LAS bf16x8*)(Ks + l31 * AT_KS + 16 * ks + 8 * hi), k1 = *(const LAS bf16x8*)(Ks + (32 + l31) * AT_KS + 16 * ks + 8 * hi);
;         const bf16x8 qq = QLDS ? qlds[ks * 64] : qf[ks];
;         p0 = MFMA32(k0, qq, p0); p1 = MFMA32(k1, qq, p1); }
;     __builtin_amdgcn_sched_barrier(0);
;     if (diag) {
;         int qp = qpos - kv0; asm volatile("" : "+v"(qp));
; #pragma unroll
;         for (int r = 0; r < 16; ++r) { const int kv = crow(r, hi); if (kv > qp) p0[r] = -INFINITY; if (kv + 32 > qp) p1[r] = -INFINITY; }
;     }
; __device__ __forceinline__ void pload_a(PRegs& R, const Args& a, int b, int h, int t, const float* cbase, int tid) {
;     const int kvl = tid >> 3, ch = tid & 7, kp = tid >> 4, c4 = tid & 15;
;     const size_t rowbase = (size_t)(b * 2048 + 64 * t);
;     const bf16_t* qkv = (const bf16_t*)(a.ws + WS_PROJ);
;     gld16(R.k, qkv + (rowbase + kvl) * NPJ + 1024 + h * 64 + 8 * ch);
;     const bf16_t* vptr = qkv + (rowbase + 2 * kp) * NPJ + 2048 + h * 64 + 4 * c4;
;     gld8(R.v0, vptr); gld8(R.v1, vptr + NPJ);
;     gld4(R.ck, cbase + 64 * t + (tid & 63));
; }
.LBB0_1691:
	s_or_b64 exec, exec, s[74:75]
	s_add_i32 s14, s91, 2
	s_max_i32 s14, s14, 0
	s_lshl_b32 s74, s14, 6
	s_add_i32 s14, s74, s58
	v_lshl_add_u64 v[50:51], s[14:15], 0, v[118:119]
	v_mov_b64_e32 v[52:53], s[72:73]
	v_mad_u64_u32 v[52:53], s[94:95], v50, s81, v[52:53]
	v_mad_i32_i24 v53, v51, s81, v53
	v_lshl_add_u64 v[50:51], v[52:53], 0, v[66:67]
	v_lshl_add_u64 v[50:51], v[50:51], 0, s[52:53]
	global_load_dwordx4 v[100:103], v[50:51], off
	v_lshl_add_u64 v[50:51], s[14:15], 0, v[120:121]
	v_mov_b64_e32 v[52:53], s[26:27]
	v_mad_u64_u32 v[52:53], s[94:95], v50, s81, v[52:53]
	v_mad_i32_i24 v53, v51, s81, v53
	s_mov_b32 s71, s15
	v_lshl_add_u64 v[50:51], v[52:53], 0, s[70:71]
	v_mov_b32_e32 v123, v67
	v_lshl_add_u64 v[50:51], v[50:51], 0, v[122:123]
	s_add_i32 s14, s77, 1
	v_lshl_add_u64 v[52:53], v[50:51], 0, s[42:43]
	v_lshl_add_u64 v[50:51], v[50:51], 0, s[54:55]
	s_mov_b32 s75, s15
	s_cmp_ge_u32 s14, s59
	global_load_dwordx2 v[124:125], v[52:53], off
	global_load_dwordx2 v[126:127], v[50:51], off
	v_lshl_add_u64 v[50:51], s[74:75], 2, v[132:133]
	global_load_dword v140, v[50:51], off
	s_waitcnt lgkmcnt(0)
	s_barrier
	s_cbranch_scc1 .LBB0_1703
	s_add_i32 s71, s92, 64
	s_cmp_gt_i32 s71, s76
	s_cbranch_scc1 .LBB0_1700
	s_add_i32 s71, s91, 5
	s_bitcmp1_b32 s14, 0
	s_cselect_b32 s14, 0x4800, 0
	s_add_i32 s14, s14, 0
	v_lshl_add_u32 v50, v139, 3, s14
	v_add_u32_e32 v50, 0x4000, v50
	ds_read2_b64 v[68:71], v50 offset0:192 offset1:224
	v_mov_b32_e32 v74, v67
	v_mov_b32_e32 v75, v67
	v_mov_b32_e32 v208, v67
	v_mov_b32_e32 v209, v67
	s_waitcnt lgkmcnt(0)
	v_and_b32_e32 v72, v68, v147
	v_and_b32_e32 v73, v69, v147
	v_and_b32_e32 v206, v70, v147
	v_and_b32_e32 v207, v71, v147
	v_lshlrev_b32_e32 v123, 1, v145
	v_add3_u32 v205, s14, v152, v123
	v_mfma_f32_32x32x16_bf16 v[50:65], v[72:75], v[112:115], v[18:33]
	v_add3_u32 v123, s14, v153, v123
	ds_read_b128 v[210:213], v205 offset:32
	s_cmp_lt_i32 s71, s57
	v_mfma_f32_32x32x16_bf16 v[68:83], v[206:209], v[112:115], v[18:33]
	ds_read_b128 v[206:209], v205
	s_waitcnt lgkmcnt(0)
	v_mfma_f32_32x32x16_bf16 v[50:65], v[206:209], v[84:87], v[50:65]
	ds_read_b128 v[206:209], v123
	ds_read_b128 v[214:217], v123 offset:32
	s_waitcnt lgkmcnt(1)
	v_mfma_f32_32x32x16_bf16 v[68:83], v[206:209], v[84:87], v[68:83]
	v_mfma_f32_32x32x16_bf16 v[50:65], v[210:213], v[88:91], v[50:65]
	ds_read_b128 v[206:209], v205 offset:64
	ds_read_b128 v[210:213], v205 offset:96
	s_waitcnt lgkmcnt(2)
	v_mfma_f32_32x32x16_bf16 v[68:83], v[214:217], v[88:91], v[68:83]
	s_waitcnt lgkmcnt(1)
	v_mfma_f32_32x32x16_bf16 v[50:65], v[206:209], v[92:95], v[50:65]
	ds_read_b128 v[206:209], v123 offset:64
	ds_read_b128 v[214:217], v123 offset:96
	s_waitcnt lgkmcnt(1)
	v_mfma_f32_32x32x16_bf16 v[68:83], v[206:209], v[92:95], v[68:83]
	v_mfma_f32_32x32x16_bf16 v[50:65], v[210:213], v[96:99], v[50:65]
	s_waitcnt lgkmcnt(0)
	v_mfma_f32_32x32x16_bf16 v[68:83], v[214:217], v[96:99], v[68:83]
	s_cbranch_scc1 .LBB0_1695
	v_subrev_u32_e32 v123, 64, v200
	s_nop 0
	v_cmp_le_i32_e64 s[98:99], v154, v123
	v_cmp_lt_i32_e64 s[100:101], v146, v123
	v_cmp_le_i32_e32 vcc, v146, v123
	s_nop 7
	v_cndmask_b32_e64 v68, v149, v68, s[98:99]
	v_cndmask_b32_e64 v51, v149, v51, s[100:101]
	v_cndmask_b32_e32 v50, v149, v50, vcc
	v_cmp_le_i32_e64 s[98:99], v155, v123
	v_cmp_le_i32_e64 s[100:101], v156, v123
	v_cmp_le_i32_e32 vcc, v157, v123
	v_cndmask_b32_e64 v69, v149, v69, s[98:99]
	v_cndmask_b32_e64 v52, v149, v52, s[100:101]
	v_cndmask_b32_e32 v70, v149, v70, vcc
	v_cmp_le_i32_e64 s[98:99], v158, v123
	v_cmp_le_i32_e64 s[100:101], v159, v123
	v_cmp_le_i32_e32 vcc, v160, v123
	v_cndmask_b32_e64 v53, v149, v53, s[98:99]
	v_cndmask_b32_e64 v71, v149, v71, s[100:101]
	v_cndmask_b32_e32 v54, v149, v54, vcc
	v_cmp_le_i32_e64 s[98:99], v161, v123
	v_cmp_le_i32_e64 s[100:101], v162, v123
	v_cmp_le_i32_e32 vcc, v163, v123
	v_cndmask_b32_e64 v72, v149, v72, s[98:99]
	v_cndmask_b32_e64 v55, v149, v55, s[100:101]
	v_cndmask_b32_e32 v73, v149, v73, vcc
	v_cmp_le_i32_e64 s[98:99], v164, v123
	v_cmp_le_i32_e64 s[100:101], v165, v123
	v_cmp_le_i32_e32 vcc, v166, v123
	v_cndmask_b32_e64 v56, v149, v56, s[98:99]
	v_cndmask_b32_e64 v74, v149, v74, s[100:101]
	v_cndmask_b32_e32 v57, v149, v57, vcc
	v_cmp_le_i32_e64 s[98:99], v167, v123
	v_cmp_le_i32_e64 s[100:101], v183, v123
	v_cmp_le_i32_e32 vcc, v184, v123
	v_cndmask_b32_e64 v75, v149, v75, s[98:99]
	v_cndmask_b32_e64 v58, v149, v58, s[100:101]
	v_cndmask_b32_e32 v76, v149, v76, vcc
	v_cmp_le_i32_e64 s[98:99], v185, v123
	v_cmp_le_i32_e64 s[100:101], v186, v123
	v_cmp_le_i32_e32 vcc, v187, v123
	v_cndmask_b32_e64 v59, v149, v59, s[98:99]
	v_cndmask_b32_e64 v77, v149, v77, s[100:101]
	v_cndmask_b32_e32 v60, v149, v60, vcc
	v_cmp_le_i32_e64 s[98:99], v188, v123
	v_cmp_le_i32_e64 s[100:101], v189, v123
	v_cmp_le_i32_e32 vcc, v190, v123
	v_cndmask_b32_e64 v78, v149, v78, s[98:99]
	v_cndmask_b32_e64 v61, v149, v61, s[100:101]
	v_cndmask_b32_e32 v79, v149, v79, vcc
	v_cmp_le_i32_e64 s[98:99], v191, v123
	v_cmp_le_i32_e64 s[100:101], v192, v123
	v_cmp_le_i32_e32 vcc, v193, v123
	v_cndmask_b32_e64 v62, v149, v62, s[98:99]
	v_cndmask_b32_e64 v80, v149, v80, s[100:101]
	v_cndmask_b32_e32 v63, v149, v63, vcc
	v_cmp_le_i32_e64 s[98:99], v194, v123
	v_cmp_le_i32_e64 s[100:101], v195, v123
	v_cmp_le_i32_e32 vcc, v196, v123
	v_cndmask_b32_e64 v81, v149, v81, s[98:99]
	v_cndmask_b32_e64 v64, v149, v64, s[100:101]
	v_cndmask_b32_e32 v82, v149, v82, vcc
	v_cmp_le_i32_e64 s[98:99], v197, v123
	v_cmp_le_i32_e32 vcc, v198, v123
	s_nop 0
	v_cndmask_b32_e64 v65, v149, v65, s[98:99]
	v_cndmask_b32_e32 v83, v149, v83, vcc

; #define LAS __attribute__((address_space(3)))
; __device__ __forceinline__ int crow(int r, int hi) { return (r & 3) + 8 * (r >> 2) + 4 * hi; }
; #define MFMA32(a, b, c) __builtin_amdgcn_mfma_f32_32x32x16_bf16((a), (b), (c), 0, 0, 0)
; template <bool QLDS> __device__ __forceinline__ void attn_tile(const LAS unsigned char* buf, const bf16x8 (&qf)[4], const LAS bf16x8* qlds, float cq2, int qpos, int kv0, bool diag, float& mrun, float& lrun, f32x16 (&ot)[2], int l31, int hi) {
;     ...
;     f32x16 p0, p1;
; #pragma unroll
;     for (int r = 0; r < 16; ++r) { p0[r] = cq2; p1[r] = cq2; }
;     {
;         const u32x2 b0 = CKs[l31], b1 = CKs[32 + l31];
;         const unsigned msk = hi ? 0u : 0xffffffffu;
;         u32x4 x0; x0.x = b0.x & msk; x0.y = b0.y & msk; x0.z = 0u; x0.w = 0u;
;         u32x4 x1; x1.x = b1.x & msk; x1.y = b1.y & msk; x1.z = 0u; x1.w = 0u;
;         u32x4 qx; qx.x = 0x3F803F80u & msk; qx.y = 0x00003F80u & msk; qx.z = 0u; qx.w = 0u;
;         p0 = MFMA32(__builtin_bit_cast(bf16x8, x0), __builtin_bit_cast(bf16x8, qx), p0); p1 = MFMA32(__builtin_bit_cast(bf16x8, x1), __builtin_bit_cast(bf16x8, qx), p1);
;     }
; #pragma unroll
;     for (int ks = 0; ks < 4; ++ks) { const bf16x8 k0 = *(const LAS bf16x8*)(Ks + l31 * AT_KS + 16 * ks + 8 * hi), k1 = *(const LAS bf16x8*)(Ks + (32 + l31) * AT_KS + 16 * ks + 8 * hi);
;         const bf16x8 qq = QLDS ? qlds[ks * 64] : qf[ks];
;         p0 = MFMA32(k0, qq, p0); p1 = MFMA32(k1, qq, p1); }
;     __builtin_amdgcn_sched_barrier(0);
;     if (diag) {
;         int qp = qpos - kv0; asm volatile("" : "+v"(qp));
; #pragma unroll
;         for (int r = 0; r < 16; ++r) { const int kv = crow(r, hi); if (kv > qp) p0[r] = -INFINITY; if (kv + 32 > qp) p1[r] = -INFINITY; }
;     }
.LBB0_1703:
	s_add_i32 s14, s77, 2
	s_cmp_ge_u32 s14, s59
	s_cbranch_scc1 .LBB0_1680
	s_cmp_gt_i32 s92, s76
	s_cbranch_scc1 .LBB0_1712
	s_add_i32 s71, s91, 4
	s_bitcmp1_b32 s77, 0
	s_cselect_b32 s14, 0x4800, 0
	s_add_i32 s14, s14, 0
	v_lshl_add_u32 v50, v139, 3, s14
	v_add_u32_e32 v50, 0x4000, v50
	ds_read2_b64 v[68:71], v50 offset0:192 offset1:224
	v_mov_b32_e32 v74, v67
	v_mov_b32_e32 v75, v67
	v_mov_b32_e32 v208, v67
	v_mov_b32_e32 v209, v67
	s_waitcnt lgkmcnt(0)
	v_and_b32_e32 v72, v68, v147
	v_and_b32_e32 v73, v69, v147
	v_and_b32_e32 v206, v70, v147
	v_and_b32_e32 v207, v71, v147
	v_lshlrev_b32_e32 v123, 1, v145
	v_add3_u32 v205, s14, v152, v123
	v_mfma_f32_32x32x16_bf16 v[50:65], v[72:75], v[112:115], v[18:33]
	v_add3_u32 v123, s14, v153, v123
	ds_read_b128 v[210:213], v205 offset:32
	s_cmp_lt_i32 s71, s57
	v_mfma_f32_32x32x16_bf16 v[68:83], v[206:209], v[112:115], v[18:33]
	ds_read_b128 v[206:209], v205
	s_waitcnt lgkmcnt(0)
	v_mfma_f32_32x32x16_bf16 v[50:65], v[206:209], v[84:87], v[50:65]
	ds_read_b128 v[206:209], v123
	ds_read_b128 v[214:217], v123 offset:32
	s_waitcnt lgkmcnt(1)
	v_mfma_f32_32x32x16_bf16 v[68:83], v[206:209], v[84:87], v[68:83]
	v_mfma_f32_32x32x16_bf16 v[50:65], v[210:213], v[88:91], v[50:65]
	ds_read_b128 v[206:209], v205 offset:64
	ds_read_b128 v[210:213], v205 offset:96
	s_waitcnt lgkmcnt(2)
	v_mfma_f32_32x32x16_bf16 v[68:83], v[214:217], v[88:91], v[68:83]
	s_waitcnt lgkmcnt(1)
	v_mfma_f32_32x32x16_bf16 v[50:65], v[206:209], v[92:95], v[50:65]
	ds_read_b128 v[206:209], v123 offset:64
	ds_read_b128 v[214:217], v123 offset:96
	s_waitcnt lgkmcnt(1)
	v_mfma_f32_32x32x16_bf16 v[68:83], v[206:209], v[92:95], v[68:83]
	v_mfma_f32_32x32x16_bf16 v[50:65], v[210:213], v[96:99], v[50:65]
	s_waitcnt lgkmcnt(0)
	v_mfma_f32_32x32x16_bf16 v[68:83], v[214:217], v[96:99], v[68:83]
	s_cbranch_scc1 .LBB0_1707
	v_mov_b32_e32 v123, v200
	s_nop 0
	v_cmp_le_i32_e64 s[98:99], v154, v123
	v_cmp_lt_i32_e64 s[100:101], v146, v123
	v_cmp_le_i32_e32 vcc, v146, v123
	s_nop 7
	v_cndmask_b32_e64 v68, v149, v68, s[98:99]
	v_cndmask_b32_e64 v51, v149, v51, s[100:101]
	v_cndmask_b32_e32 v50, v149, v50, vcc
	v_cmp_le_i32_e64 s[98:99], v155, v123
	v_cmp_le_i32_e64 s[100:101], v156, v123
	v_cmp_le_i32_e32 vcc, v157, v123
	v_cndmask_b32_e64 v69, v149, v69, s[98:99]
	v_cndmask_b32_e64 v52, v149, v52, s[100:101]
	v_cndmask_b32_e32 v70, v149, v70, vcc
	v_cmp_le_i32_e64 s[98:99], v158, v123
	v_cmp_le_i32_e64 s[100:101], v159, v123
	v_cmp_le_i32_e32 vcc, v160, v123
	v_cndmask_b32_e64 v53, v149, v53, s[98:99]
	v_cndmask_b32_e64 v71, v149, v71, s[100:101]
	v_cndmask_b32_e32 v54, v149, v54, vcc
	v_cmp_le_i32_e64 s[98:99], v161, v123
	v_cmp_le_i32_e64 s[100:101], v162, v123
	v_cmp_le_i32_e32 vcc, v163, v123
	v_cndmask_b32_e64 v72, v149, v72, s[98:99]
	v_cndmask_b32_e64 v55, v149, v55, s[100:101]
	v_cndmask_b32_e32 v73, v149, v73, vcc
	v_cmp_le_i32_e64 s[98:99], v164, v123
	v_cmp_le_i32_e64 s[100:101], v165, v123
	v_cmp_le_i32_e32 vcc, v166, v123
	v_cndmask_b32_e64 v56, v149, v56, s[98:99]
	v_cndmask_b32_e64 v74, v149, v74, s[100:101]
	v_cndmask_b32_e32 v57, v149, v57, vcc
	v_cmp_le_i32_e64 s[98:99], v167, v123
	v_cmp_le_i32_e64 s[100:101], v183, v123
	v_cmp_le_i32_e32 vcc, v184, v123
	v_cndmask_b32_e64 v75, v149, v75, s[98:99]
	v_cndmask_b32_e64 v58, v149, v58, s[100:101]
	v_cndmask_b32_e32 v76, v149, v76, vcc
	v_cmp_le_i32_e64 s[98:99], v185, v123
	v_cmp_le_i32_e64 s[100:101], v186, v123
	v_cmp_le_i32_e32 vcc, v187, v123
	v_cndmask_b32_e64 v59, v149, v59, s[98:99]
	v_cndmask_b32_e64 v77, v149, v77, s[100:101]
	v_cndmask_b32_e32 v60, v149, v60, vcc
	v_cmp_le_i32_e64 s[98:99], v188, v123
	v_cmp_le_i32_e64 s[100:101], v189, v123
	v_cmp_le_i32_e32 vcc, v190, v123
	v_cndmask_b32_e64 v78, v149, v78, s[98:99]
	v_cndmask_b32_e64 v61, v149, v61, s[100:101]
	v_cndmask_b32_e32 v79, v149, v79, vcc
	v_cmp_le_i32_e64 s[98:99], v191, v123
	v_cmp_le_i32_e64 s[100:101], v192, v123
	v_cmp_le_i32_e32 vcc, v193, v123
	v_cndmask_b32_e64 v62, v149, v62, s[98:99]
	v_cndmask_b32_e64 v80, v149, v80, s[100:101]
	v_cndmask_b32_e32 v63, v149, v63, vcc
	v_cmp_le_i32_e64 s[98:99], v194, v123
	v_cmp_le_i32_e64 s[100:101], v195, v123
	v_cmp_le_i32_e32 vcc, v196, v123
	v_cndmask_b32_e64 v81, v149, v81, s[98:99]
	v_cndmask_b32_e64 v64, v149, v64, s[100:101]
	v_cndmask_b32_e32 v82, v149, v82, vcc
	v_cmp_le_i32_e64 s[98:99], v197, v123
	v_cmp_le_i32_e32 vcc, v198, v123
	s_nop 0
	v_cndmask_b32_e64 v65, v149, v65, s[98:99]
	v_cndmask_b32_e32 v83, v149, v83, vcc

; #define LAS __attribute__((address_space(3)))
; __device__ __forceinline__ int crow(int r, int hi) { return (r & 3) + 8 * (r >> 2) + 4 * hi; }
; #define MFMA32(a, b, c) __builtin_amdgcn_mfma_f32_32x32x16_bf16((a), (b), (c), 0, 0, 0)
; template <bool QLDS> __device__ __forceinline__ void attn_tile(const LAS unsigned char* buf, const bf16x8 (&qf)[4], const LAS bf16x8* qlds, float cq2, int qpos, int kv0, bool diag, float& mrun, float& lrun, f32x16 (&ot)[2], int l31, int hi) {
;     ...
;     f32x16 p0, p1;
; #pragma unroll
;     for (int r = 0; r < 16; ++r) { p0[r] = cq2; p1[r] = cq2; }
;     {
;         const u32x2 b0 = CKs[l31], b1 = CKs[32 + l31];
;         const unsigned msk = hi ? 0u : 0xffffffffu;
;         u32x4 x0; x0.x = b0.x & msk; x0.y = b0.y & msk; x0.z = 0u; x0.w = 0u;
;         u32x4 x1; x1.x = b1.x & msk; x1.y = b1.y & msk; x1.z = 0u; x1.w = 0u;
;         u32x4 qx; qx.x = 0x3F803F80u & msk; qx.y = 0x00003F80u & msk; qx.z = 0u; qx.w = 0u;
;         p0 = MFMA32(__builtin_bit_cast(bf16x8, x0), __builtin_bit_cast(bf16x8, qx), p0); p1 = MFMA32(__builtin_bit_cast(bf16x8, x1), __builtin_bit_cast(bf16x8, qx), p1);
;     }
; #pragma unroll
;     for (int ks = 0; ks < 4; ++ks) { const bf16x8 k0 = *(const LAS bf16x8*)(Ks + l31 * AT_KS + 16 * ks + 8 * hi), k1 = *(const LAS bf16x8*)(Ks + (32 + l31) * AT_KS + 16 * ks + 8 * hi);
;         const bf16x8 qq = QLDS ? qlds[ks * 64] : qf[ks];
;         p0 = MFMA32(k0, qq, p0); p1 = MFMA32(k1, qq, p1); }
;     __builtin_amdgcn_sched_barrier(0);
;     if (diag) {
;         int qp = qpos - kv0; asm volatile("" : "+v"(qp));
; #pragma unroll
;         for (int r = 0; r < 16; ++r) { const int kv = crow(r, hi); if (kv > qp) p0[r] = -INFINITY; if (kv + 32 > qp) p1[r] = -INFINITY; }
;     }
.LBB0_1724:
	s_add_i32 s70, s74, 64
	s_cmp_gt_i32 s70, s72
	s_cbranch_scc1 .LBB0_1732
	s_add_i32 s71, s73, 6
	s_bitcmp1_b32 s58, 0
	s_cselect_b32 s70, 0x4800, 0
	s_add_i32 s70, s70, 0
	v_lshl_add_u32 v68, v121, 3, s70
	v_add_u32_e32 v68, 0x4000, v68
	ds_read2_b64 v[82:85], v68 offset0:192 offset1:224
	v_mov_b32_e32 v88, v67
	v_mov_b32_e32 v89, v67
	v_mov_b32_e32 v204, v67
	v_mov_b32_e32 v205, v67
	s_waitcnt lgkmcnt(0)
	v_and_b32_e32 v86, v82, v151
	v_and_b32_e32 v87, v83, v151
	v_and_b32_e32 v202, v84, v151
	v_and_b32_e32 v203, v85, v151
	v_lshlrev_b32_e32 v129, 1, v147
	v_add3_u32 v214, s70, v152, v129
	v_mfma_f32_32x32x16_bf16 v[68:83], v[86:89], v[116:119], v[36:51]
	v_add3_u32 v129, s70, v153, v129
	ds_read_b128 v[206:209], v214 offset:32
	s_cmp_lt_i32 s71, s57
	v_mfma_f32_32x32x16_bf16 v[84:99], v[202:205], v[116:119], v[36:51]
	ds_read_b128 v[202:205], v214
	s_waitcnt lgkmcnt(0)
	v_mfma_f32_32x32x16_bf16 v[68:83], v[202:205], v[52:55], v[68:83]
	ds_read_b128 v[202:205], v129
	ds_read_b128 v[210:213], v129 offset:32
	s_waitcnt lgkmcnt(1)
	v_mfma_f32_32x32x16_bf16 v[84:99], v[202:205], v[52:55], v[84:99]
	v_mfma_f32_32x32x16_bf16 v[68:83], v[206:209], v[56:59], v[68:83]
	ds_read_b128 v[202:205], v214 offset:64
	ds_read_b128 v[206:209], v214 offset:96
	s_waitcnt lgkmcnt(2)
	v_mfma_f32_32x32x16_bf16 v[84:99], v[210:213], v[56:59], v[84:99]
	s_waitcnt lgkmcnt(1)
	v_mfma_f32_32x32x16_bf16 v[68:83], v[202:205], v[60:63], v[68:83]
	ds_read_b128 v[202:205], v129 offset:64
	ds_read_b128 v[210:213], v129 offset:96
	s_waitcnt lgkmcnt(1)
	v_mfma_f32_32x32x16_bf16 v[84:99], v[202:205], v[60:63], v[84:99]
	v_mfma_f32_32x32x16_bf16 v[68:83], v[206:209], v[100:103], v[68:83]
	s_waitcnt lgkmcnt(0)
	v_mfma_f32_32x32x16_bf16 v[84:99], v[210:213], v[100:103], v[84:99]
	s_cbranch_scc1 .LBB0_1727
	v_add_u32_e32 v129, 0xffffff80, v200
	s_nop 0
	v_cmp_le_i32_e64 s[98:99], v154, v129
	v_cmp_lt_i32_e64 s[100:101], v146, v129
	v_cmp_le_i32_e32 vcc, v146, v129
	s_nop 7
	v_cndmask_b32_e64 v84, v149, v84, s[98:99]
	v_cndmask_b32_e64 v69, v149, v69, s[100:101]
	v_cndmask_b32_e32 v68, v149, v68, vcc
	v_cmp_le_i32_e64 s[98:99], v155, v129
	v_cmp_le_i32_e64 s[100:101], v156, v129
	v_cmp_le_i32_e32 vcc, v157, v129
	v_cndmask_b32_e64 v85, v149, v85, s[98:99]
	v_cndmask_b32_e64 v70, v149, v70, s[100:101]
	v_cndmask_b32_e32 v86, v149, v86, vcc
	v_cmp_le_i32_e64 s[98:99], v158, v129
	v_cmp_le_i32_e64 s[100:101], v159, v129
	v_cmp_le_i32_e32 vcc, v160, v129
	v_cndmask_b32_e64 v71, v149, v71, s[98:99]
	v_cndmask_b32_e64 v87, v149, v87, s[100:101]
	v_cndmask_b32_e32 v72, v149, v72, vcc
	v_cmp_le_i32_e64 s[98:99], v161, v129
	v_cmp_le_i32_e64 s[100:101], v162, v129
	v_cmp_le_i32_e32 vcc, v163, v129
	v_cndmask_b32_e64 v88, v149, v88, s[98:99]
	v_cndmask_b32_e64 v73, v149, v73, s[100:101]
	v_cndmask_b32_e32 v89, v149, v89, vcc
	v_cmp_le_i32_e64 s[98:99], v164, v129
	v_cmp_le_i32_e64 s[100:101], v165, v129
	v_cmp_le_i32_e32 vcc, v166, v129
	v_cndmask_b32_e64 v74, v149, v74, s[98:99]
	v_cndmask_b32_e64 v90, v149, v90, s[100:101]
	v_cndmask_b32_e32 v75, v149, v75, vcc
	v_cmp_le_i32_e64 s[98:99], v167, v129
	v_cmp_le_i32_e64 s[100:101], v183, v129
	v_cmp_le_i32_e32 vcc, v184, v129
	v_cndmask_b32_e64 v91, v149, v91, s[98:99]
	v_cndmask_b32_e64 v76, v149, v76, s[100:101]
	v_cndmask_b32_e32 v92, v149, v92, vcc
	v_cmp_le_i32_e64 s[98:99], v185, v129
	v_cmp_le_i32_e64 s[100:101], v186, v129
	v_cmp_le_i32_e32 vcc, v187, v129
	v_cndmask_b32_e64 v77, v149, v77, s[98:99]
	v_cndmask_b32_e64 v93, v149, v93, s[100:101]
	v_cndmask_b32_e32 v78, v149, v78, vcc
	v_cmp_le_i32_e64 s[98:99], v188, v129
	v_cmp_le_i32_e64 s[100:101], v189, v129
	v_cmp_le_i32_e32 vcc, v190, v129
	v_cndmask_b32_e64 v94, v149, v94, s[98:99]
	v_cndmask_b32_e64 v79, v149, v79, s[100:101]
	v_cndmask_b32_e32 v95, v149, v95, vcc
	v_cmp_le_i32_e64 s[98:99], v191, v129
	v_cmp_le_i32_e64 s[100:101], v192, v129
	v_cmp_le_i32_e32 vcc, v193, v129
	v_cndmask_b32_e64 v80, v149, v80, s[98:99]
	v_cndmask_b32_e64 v96, v149, v96, s[100:101]
	v_cndmask_b32_e32 v81, v149, v81, vcc
	v_cmp_le_i32_e64 s[98:99], v194, v129
	v_cmp_le_i32_e64 s[100:101], v195, v129
	v_cmp_le_i32_e32 vcc, v196, v129
	v_cndmask_b32_e64 v97, v149, v97, s[98:99]
	v_cndmask_b32_e64 v82, v149, v82, s[100:101]
	v_cndmask_b32_e32 v98, v149, v98, vcc
	v_cmp_le_i32_e64 s[98:99], v197, v129
	v_cmp_le_i32_e32 vcc, v198, v129
	s_nop 0
	v_cndmask_b32_e64 v83, v149, v83, s[98:99]
	v_cndmask_b32_e32 v99, v149, v99, vcc

; #define LAS __attribute__((address_space(3)))
; __device__ __forceinline__ int crow(int r, int hi) { return (r & 3) + 8 * (r >> 2) + 4 * hi; }
; #define MFMA32(a, b, c) __builtin_amdgcn_mfma_f32_32x32x16_bf16((a), (b), (c), 0, 0, 0)
; template <bool QLDS> __device__ __forceinline__ void attn_tile(const LAS unsigned char* buf, const bf16x8 (&qf)[4], const LAS bf16x8* qlds, float cq2, int qpos, int kv0, bool diag, float& mrun, float& lrun, f32x16 (&ot)[2], int l31, int hi) {
;     ...
;     f32x16 p0, p1;
; #pragma unroll
;     for (int r = 0; r < 16; ++r) { p0[r] = cq2; p1[r] = cq2; }
;     {
;         const u32x2 b0 = CKs[l31], b1 = CKs[32 + l31];
;         const unsigned msk = hi ? 0u : 0xffffffffu;
;         u32x4 x0; x0.x = b0.x & msk; x0.y = b0.y & msk; x0.z = 0u; x0.w = 0u;
;         u32x4 x1; x1.x = b1.x & msk; x1.y = b1.y & msk; x1.z = 0u; x1.w = 0u;
;         u32x4 qx; qx.x = 0x3F803F80u & msk; qx.y = 0x00003F80u & msk; qx.z = 0u; qx.w = 0u;
;         p0 = MFMA32(__builtin_bit_cast(bf16x8, x0), __builtin_bit_cast(bf16x8, qx), p0); p1 = MFMA32(__builtin_bit_cast(bf16x8, x1), __builtin_bit_cast(bf16x8, qx), p1);
;     }
; #pragma unroll
;     for (int ks = 0; ks < 4; ++ks) { const bf16x8 k0 = *(const LAS bf16x8*)(Ks + l31 * AT_KS + 16 * ks + 8 * hi), k1 = *(const LAS bf16x8*)(Ks + (32 + l31) * AT_KS + 16 * ks + 8 * hi);
;         const bf16x8 qq = QLDS ? qlds[ks * 64] : qf[ks];
;         p0 = MFMA32(k0, qq, p0); p1 = MFMA32(k1, qq, p1); }
;     __builtin_amdgcn_sched_barrier(0);
;     if (diag) {
;         int qp = qpos - kv0; asm volatile("" : "+v"(qp));
; #pragma unroll
;         for (int r = 0; r < 16; ++r) { const int kv = crow(r, hi); if (kv > qp) p0[r] = -INFINITY; if (kv + 32 > qp) p1[r] = -INFINITY; }
;     }
; __device__ __forceinline__ void pload_a(PRegs& R, const Args& a, int b, int h, int t, const float* cbase, int tid) {
;     const int kvl = tid >> 3, ch = tid & 7, kp = tid >> 4, c4 = tid & 15;
;     const size_t rowbase = (size_t)(b * 2048 + 64 * t);
;     const bf16_t* qkv = (const bf16_t*)(a.ws + WS_PROJ);
;     gld16(R.k, qkv + (rowbase + kvl) * NPJ + 1024 + h * 64 + 8 * ch);
;     const bf16_t* vptr = qkv + (rowbase + 2 * kp) * NPJ + 2048 + h * 64 + 4 * c4;
;     gld8(R.v0, vptr); gld8(R.v1, vptr + NPJ);
;     gld4(R.ck, cbase + 64 * t + (tid & 63));
; }
.LBB0_1734:
	s_or_b64 exec, exec, s[70:71]
	s_add_i32 s70, s73, 2
	s_max_i32 s70, s70, 0
	s_lshl_b32 s70, s70, 6
	s_add_i32 s76, s70, s61
	s_ashr_i32 s77, s76, 31
	v_lshl_add_u64 v[68:69], s[76:77], 0, v[64:65]
	v_mov_b64_e32 v[70:71], s[22:23]
	v_mad_u64_u32 v[70:71], s[92:93], v68, s81, v[70:71]
	v_mad_i32_i24 v71, v69, s81, v71
	v_lshl_add_u64 v[68:69], v[70:71], 0, v[66:67]
	v_lshl_add_u64 v[68:69], v[68:69], 0, s[52:53]
	global_load_dwordx4 v[104:107], v[68:69], off
	v_lshl_add_u64 v[68:69], s[76:77], 0, v[122:123]
	v_mov_b64_e32 v[70:71], s[26:27]
	v_mad_u64_u32 v[70:71], s[76:77], v68, s81, v[70:71]
	v_mad_i32_i24 v71, v69, s81, v71
	v_lshl_add_u64 v[68:69], v[70:71], 0, s[14:15]
	v_mov_b32_e32 v129, v67
	v_lshl_add_u64 v[68:69], v[68:69], 0, v[128:129]
	v_lshl_add_u64 v[70:71], v[68:69], 0, s[42:43]
	v_lshl_add_u64 v[68:69], v[68:69], 0, s[54:55]
	s_mov_b32 s71, s15
	global_load_dwordx2 v[124:125], v[70:71], off
	global_load_dwordx2 v[126:127], v[68:69], off
	v_lshl_add_u64 v[68:69], s[70:71], 2, v[138:139]
	s_add_i32 s70, s58, 1
	s_cmp_ge_i32 s70, s59
	global_load_dword v140, v[68:69], off
	s_waitcnt lgkmcnt(0)
	s_barrier
	s_cbranch_scc1 .LBB0_1746
	s_cmp_gt_i32 s74, s72
	s_cbranch_scc1 .LBB0_1743
	s_add_i32 s71, s73, 5
	s_bitcmp1_b32 s70, 0
	s_cselect_b32 s70, 0x4800, 0
	s_add_i32 s70, s70, 0
	v_lshl_add_u32 v68, v121, 3, s70
	v_add_u32_e32 v68, 0x4000, v68
	ds_read2_b64 v[82:85], v68 offset0:192 offset1:224
	v_mov_b32_e32 v88, v67
	v_mov_b32_e32 v89, v67
	v_mov_b32_e32 v206, v67
	v_mov_b32_e32 v207, v67
	s_waitcnt lgkmcnt(0)
	v_and_b32_e32 v86, v82, v151
	v_and_b32_e32 v87, v83, v151
	v_and_b32_e32 v204, v84, v151
	v_and_b32_e32 v205, v85, v151
	v_lshlrev_b32_e32 v129, 1, v147
	v_add3_u32 v216, s70, v152, v129
	v_mfma_f32_32x32x16_bf16 v[68:83], v[86:89], v[116:119], v[36:51]
	v_add3_u32 v129, s70, v153, v129
	ds_read_b128 v[208:211], v216 offset:32
	s_cmp_lt_i32 s71, s57
	v_mfma_f32_32x32x16_bf16 v[84:99], v[204:207], v[116:119], v[36:51]
	ds_read_b128 v[204:207], v216
	s_waitcnt lgkmcnt(0)
	v_mfma_f32_32x32x16_bf16 v[68:83], v[204:207], v[52:55], v[68:83]
	ds_read_b128 v[204:207], v129
	ds_read_b128 v[212:215], v129 offset:32
	s_waitcnt lgkmcnt(1)
	v_mfma_f32_32x32x16_bf16 v[84:99], v[204:207], v[52:55], v[84:99]
	v_mfma_f32_32x32x16_bf16 v[68:83], v[208:211], v[56:59], v[68:83]
	ds_read_b128 v[204:207], v216 offset:64
	ds_read_b128 v[208:211], v216 offset:96
	s_waitcnt lgkmcnt(2)
	v_mfma_f32_32x32x16_bf16 v[84:99], v[212:215], v[56:59], v[84:99]
	s_waitcnt lgkmcnt(1)
	v_mfma_f32_32x32x16_bf16 v[68:83], v[204:207], v[60:63], v[68:83]
	ds_read_b128 v[204:207], v129 offset:64
	ds_read_b128 v[212:215], v129 offset:96
	s_waitcnt lgkmcnt(1)
	v_mfma_f32_32x32x16_bf16 v[84:99], v[204:207], v[60:63], v[84:99]
	v_mfma_f32_32x32x16_bf16 v[68:83], v[208:211], v[100:103], v[68:83]
	s_waitcnt lgkmcnt(0)
	v_mfma_f32_32x32x16_bf16 v[84:99], v[212:215], v[100:103], v[84:99]
	s_cbranch_scc1 .LBB0_1738
	v_subrev_u32_e32 v129, 64, v200
	s_nop 0
	v_cmp_le_i32_e64 s[98:99], v154, v129
	v_cmp_lt_i32_e64 s[100:101], v146, v129
	v_cmp_le_i32_e32 vcc, v146, v129
	s_nop 7
	v_cndmask_b32_e64 v84, v149, v84, s[98:99]
	v_cndmask_b32_e64 v69, v149, v69, s[100:101]
	v_cndmask_b32_e32 v68, v149, v68, vcc
	v_cmp_le_i32_e64 s[98:99], v155, v129
	v_cmp_le_i32_e64 s[100:101], v156, v129
	v_cmp_le_i32_e32 vcc, v157, v129
	v_cndmask_b32_e64 v85, v149, v85, s[98:99]
	v_cndmask_b32_e64 v70, v149, v70, s[100:101]
	v_cndmask_b32_e32 v86, v149, v86, vcc
	v_cmp_le_i32_e64 s[98:99], v158, v129
	v_cmp_le_i32_e64 s[100:101], v159, v129
	v_cmp_le_i32_e32 vcc, v160, v129
	v_cndmask_b32_e64 v71, v149, v71, s[98:99]
	v_cndmask_b32_e64 v87, v149, v87, s[100:101]
	v_cndmask_b32_e32 v72, v149, v72, vcc
	v_cmp_le_i32_e64 s[98:99], v161, v129
	v_cmp_le_i32_e64 s[100:101], v162, v129
	v_cmp_le_i32_e32 vcc, v163, v129
	v_cndmask_b32_e64 v88, v149, v88, s[98:99]
	v_cndmask_b32_e64 v73, v149, v73, s[100:101]
	v_cndmask_b32_e32 v89, v149, v89, vcc
	v_cmp_le_i32_e64 s[98:99], v164, v129
	v_cmp_le_i32_e64 s[100:101], v165, v129
	v_cmp_le_i32_e32 vcc, v166, v129
	v_cndmask_b32_e64 v74, v149, v74, s[98:99]
	v_cndmask_b32_e64 v90, v149, v90, s[100:101]
	v_cndmask_b32_e32 v75, v149, v75, vcc
	v_cmp_le_i32_e64 s[98:99], v167, v129
	v_cmp_le_i32_e64 s[100:101], v183, v129
	v_cmp_le_i32_e32 vcc, v184, v129
	v_cndmask_b32_e64 v91, v149, v91, s[98:99]
	v_cndmask_b32_e64 v76, v149, v76, s[100:101]
	v_cndmask_b32_e32 v92, v149, v92, vcc
	v_cmp_le_i32_e64 s[98:99], v185, v129
	v_cmp_le_i32_e64 s[100:101], v186, v129
	v_cmp_le_i32_e32 vcc, v187, v129
	v_cndmask_b32_e64 v77, v149, v77, s[98:99]
	v_cndmask_b32_e64 v93, v149, v93, s[100:101]
	v_cndmask_b32_e32 v78, v149, v78, vcc
	v_cmp_le_i32_e64 s[98:99], v188, v129
	v_cmp_le_i32_e64 s[100:101], v189, v129
	v_cmp_le_i32_e32 vcc, v190, v129
	v_cndmask_b32_e64 v94, v149, v94, s[98:99]
	v_cndmask_b32_e64 v79, v149, v79, s[100:101]
	v_cndmask_b32_e32 v95, v149, v95, vcc
	v_cmp_le_i32_e64 s[98:99], v191, v129
	v_cmp_le_i32_e64 s[100:101], v192, v129
	v_cmp_le_i32_e32 vcc, v193, v129
	v_cndmask_b32_e64 v80, v149, v80, s[98:99]
	v_cndmask_b32_e64 v96, v149, v96, s[100:101]
	v_cndmask_b32_e32 v81, v149, v81, vcc
	v_cmp_le_i32_e64 s[98:99], v194, v129
	v_cmp_le_i32_e64 s[100:101], v195, v129
	v_cmp_le_i32_e32 vcc, v196, v129
	v_cndmask_b32_e64 v97, v149, v97, s[98:99]
	v_cndmask_b32_e64 v82, v149, v82, s[100:101]
	v_cndmask_b32_e32 v98, v149, v98, vcc
	v_cmp_le_i32_e64 s[98:99], v197, v129
	v_cmp_le_i32_e32 vcc, v198, v129
	s_nop 0
	v_cndmask_b32_e64 v83, v149, v83, s[98:99]
	v_cndmask_b32_e32 v99, v149, v99, vcc

; #define LAS __attribute__((address_space(3)))
; __device__ __forceinline__ int crow(int r, int hi) { return (r & 3) + 8 * (r >> 2) + 4 * hi; }
; #define MFMA32(a, b, c) __builtin_amdgcn_mfma_f32_32x32x16_bf16((a), (b), (c), 0, 0, 0)
; template <bool QLDS> __device__ __forceinline__ void attn_tile(const LAS unsigned char* buf, const bf16x8 (&qf)[4], const LAS bf16x8* qlds, float cq2, int qpos, int kv0, bool diag, float& mrun, float& lrun, f32x16 (&ot)[2], int l31, int hi) {
;     const LAS bf16_t* Ks = (const LAS bf16_t*)buf; const LAS bf16_t* VTs = (const LAS bf16_t*)(buf + AT_VOFF); const LAS u32x2* CKs = (const LAS u32x2*)(buf + AT_COFF);
;     f32x16 p0, p1;
; #pragma unroll
;     for (int r = 0; r < 16; ++r) { p0[r] = cq2; p1[r] = cq2; }
;     {
;         const u32x2 b0 = CKs[l31], b1 = CKs[32 + l31];
;         const unsigned msk = hi ? 0u : 0xffffffffu;
;         u32x4 x0; x0.x = b0.x & msk; x0.y = b0.y & msk; x0.z = 0u; x0.w = 0u;
;         u32x4 x1; x1.x = b1.x & msk; x1.y = b1.y & msk; x1.z = 0u; x1.w = 0u;
;         u32x4 qx; qx.x = 0x3F803F80u & msk; qx.y = 0x00003F80u & msk; qx.z = 0u; qx.w = 0u;
;         p0 = MFMA32(__builtin_bit_cast(bf16x8, x0), __builtin_bit_cast(bf16x8, qx), p0); p1 = MFMA32(__builtin_bit_cast(bf16x8, x1), __builtin_bit_cast(bf16x8, qx), p1);
;     }
; #pragma unroll
;     for (int ks = 0; ks < 4; ++ks) { const bf16x8 k0 = *(const LAS bf16x8*)(Ks + l31 * AT_KS + 16 * ks + 8 * hi), k1 = *(const LAS bf16x8*)(Ks + (32 + l31) * AT_KS + 16 * ks + 8 * hi);
;         const bf16x8 qq = QLDS ? qlds[ks * 64] : qf[ks];
;         p0 = MFMA32(k0, qq, p0); p1 = MFMA32(k1, qq, p1); }
;     __builtin_amdgcn_sched_barrier(0);
;     if (diag) {
;         int qp = qpos - kv0; asm volatile("" : "+v"(qp));
; #pragma unroll
;         for (int r = 0; r < 16; ++r) { const int kv = crow(r, hi); if (kv > qp) p0[r] = -INFINITY; if (kv + 32 > qp) p1[r] = -INFINITY; }
.LBB0_1746:
	s_add_i32 s70, s58, 2
	s_cmp_ge_i32 s70, s59
	s_cbranch_scc1 .LBB0_1723
	s_sub_i32 s70, s74, 64
	s_cmp_gt_i32 s70, s72
	s_cbranch_scc1 .LBB0_1755
	s_add_i32 s71, s73, 4
	s_bitcmp1_b32 s58, 0
	s_cselect_b32 s70, 0x4800, 0
	s_add_i32 s70, s70, 0
	v_lshl_add_u32 v68, v121, 3, s70
	v_add_u32_e32 v68, 0x4000, v68
	ds_read2_b64 v[82:85], v68 offset0:192 offset1:224
	v_mov_b32_e32 v88, v67
	v_mov_b32_e32 v89, v67
	v_mov_b32_e32 v206, v67
	v_mov_b32_e32 v207, v67
	s_waitcnt lgkmcnt(0)
	v_and_b32_e32 v86, v82, v151
	v_and_b32_e32 v87, v83, v151
	v_and_b32_e32 v204, v84, v151
	v_and_b32_e32 v205, v85, v151
	v_lshlrev_b32_e32 v129, 1, v147
	v_add3_u32 v216, s70, v152, v129
	v_mfma_f32_32x32x16_bf16 v[68:83], v[86:89], v[116:119], v[36:51]
	v_add3_u32 v129, s70, v153, v129
	ds_read_b128 v[208:211], v216 offset:32
	s_cmp_lt_i32 s71, s57
	v_mfma_f32_32x32x16_bf16 v[84:99], v[204:207], v[116:119], v[36:51]
	ds_read_b128 v[204:207], v216
	s_waitcnt lgkmcnt(0)
	v_mfma_f32_32x32x16_bf16 v[68:83], v[204:207], v[52:55], v[68:83]
	ds_read_b128 v[204:207], v129
	ds_read_b128 v[212:215], v129 offset:32
	s_waitcnt lgkmcnt(1)
	v_mfma_f32_32x32x16_bf16 v[84:99], v[204:207], v[52:55], v[84:99]
	v_mfma_f32_32x32x16_bf16 v[68:83], v[208:211], v[56:59], v[68:83]
	ds_read_b128 v[204:207], v216 offset:64
	ds_read_b128 v[208:211], v216 offset:96
	s_waitcnt lgkmcnt(2)
	v_mfma_f32_32x32x16_bf16 v[84:99], v[212:215], v[56:59], v[84:99]
	s_waitcnt lgkmcnt(1)
	v_mfma_f32_32x32x16_bf16 v[68:83], v[204:207], v[60:63], v[68:83]
	ds_read_b128 v[204:207], v129 offset:64
	ds_read_b128 v[212:215], v129 offset:96
	s_waitcnt lgkmcnt(1)
	v_mfma_f32_32x32x16_bf16 v[84:99], v[204:207], v[60:63], v[84:99]
	v_mfma_f32_32x32x16_bf16 v[68:83], v[208:211], v[100:103], v[68:83]
	s_waitcnt lgkmcnt(0)
	v_mfma_f32_32x32x16_bf16 v[84:99], v[212:215], v[100:103], v[84:99]
	s_cbranch_scc1 .LBB0_1750
	v_mov_b32_e32 v129, v200
	s_nop 0
	v_cmp_le_i32_e64 s[98:99], v154, v129
	v_cmp_lt_i32_e64 s[100:101], v146, v129
	v_cmp_le_i32_e32 vcc, v146, v129
	s_nop 7
	v_cndmask_b32_e64 v84, v149, v84, s[98:99]
	v_cndmask_b32_e64 v69, v149, v69, s[100:101]
	v_cndmask_b32_e32 v68, v149, v68, vcc
	v_cmp_le_i32_e64 s[98:99], v155, v129
	v_cmp_le_i32_e64 s[100:101], v156, v129
	v_cmp_le_i32_e32 vcc, v157, v129
	v_cndmask_b32_e64 v85, v149, v85, s[98:99]
	v_cndmask_b32_e64 v70, v149, v70, s[100:101]
	v_cndmask_b32_e32 v86, v149, v86, vcc
	v_cmp_le_i32_e64 s[98:99], v158, v129
	v_cmp_le_i32_e64 s[100:101], v159, v129
	v_cmp_le_i32_e32 vcc, v160, v129
	v_cndmask_b32_e64 v71, v149, v71, s[98:99]
	v_cndmask_b32_e64 v87, v149, v87, s[100:101]
	v_cndmask_b32_e32 v72, v149, v72, vcc
	v_cmp_le_i32_e64 s[98:99], v161, v129
	v_cmp_le_i32_e64 s[100:101], v162, v129
	v_cmp_le_i32_e32 vcc, v163, v129
	v_cndmask_b32_e64 v88, v149, v88, s[98:99]
	v_cndmask_b32_e64 v73, v149, v73, s[100:101]
	v_cndmask_b32_e32 v89, v149, v89, vcc
	v_cmp_le_i32_e64 s[98:99], v164, v129
	v_cmp_le_i32_e64 s[100:101], v165, v129
	v_cmp_le_i32_e32 vcc, v166, v129
	v_cndmask_b32_e64 v74, v149, v74, s[98:99]
	v_cndmask_b32_e64 v90, v149, v90, s[100:101]
	v_cndmask_b32_e32 v75, v149, v75, vcc
	v_cmp_le_i32_e64 s[98:99], v167, v129
	v_cmp_le_i32_e64 s[100:101], v183, v129
	v_cmp_le_i32_e32 vcc, v184, v129
	v_cndmask_b32_e64 v91, v149, v91, s[98:99]
	v_cndmask_b32_e64 v76, v149, v76, s[100:101]
	v_cndmask_b32_e32 v92, v149, v92, vcc
	v_cmp_le_i32_e64 s[98:99], v185, v129
	v_cmp_le_i32_e64 s[100:101], v186, v129
	v_cmp_le_i32_e32 vcc, v187, v129
	v_cndmask_b32_e64 v77, v149, v77, s[98:99]
	v_cndmask_b32_e64 v93, v149, v93, s[100:101]
	v_cndmask_b32_e32 v78, v149, v78, vcc
	v_cmp_le_i32_e64 s[98:99], v188, v129
	v_cmp_le_i32_e64 s[100:101], v189, v129
	v_cmp_le_i32_e32 vcc, v190, v129
	v_cndmask_b32_e64 v94, v149, v94, s[98:99]
	v_cndmask_b32_e64 v79, v149, v79, s[100:101]
	v_cndmask_b32_e32 v95, v149, v95, vcc
	v_cmp_le_i32_e64 s[98:99], v191, v129
	v_cmp_le_i32_e64 s[100:101], v192, v129
	v_cmp_le_i32_e32 vcc, v193, v129
	v_cndmask_b32_e64 v80, v149, v80, s[98:99]
	v_cndmask_b32_e64 v96, v149, v96, s[100:101]
	v_cndmask_b32_e32 v81, v149, v81, vcc
	v_cmp_le_i32_e64 s[98:99], v194, v129
	v_cmp_le_i32_e64 s[100:101], v195, v129
	v_cmp_le_i32_e32 vcc, v196, v129
	v_cndmask_b32_e64 v97, v149, v97, s[98:99]
	v_cndmask_b32_e64 v82, v149, v82, s[100:101]
	v_cndmask_b32_e32 v98, v149, v98, vcc
	v_cmp_le_i32_e64 s[98:99], v197, v129
	v_cmp_le_i32_e32 vcc, v198, v129
	s_nop 0
	v_cndmask_b32_e64 v83, v149, v83, s[98:99]
	v_cndmask_b32_e32 v99, v149, v99, vcc
